# MERGE work split by token-tile owner (group = blockIdx&7) so the MERGE->G2 barrier is XCD-local too
# speedup vs baseline: 1.0052x; 1.0052x over previous
; DI float lo_f(unsigned u) { return __uint_as_float(u << 16); }
; DI float hi_f(unsigned u) { return __uint_as_float(u & 0xffff0000u); }
; DI unsigned pk2(float lo, float hi) { return pg8::cvt_pk_bf16(lo, hi); }
; __global__ void __launch_bounds__(512, 2) fwd_mega(Args a) {
;     ...
;         for (int i = bx * 512 + tid; i < TH * 64; i += G * 512) {
;             const int tok = i >> 6, rem = i & 63, hs = rem >> 4, ch = rem & 15;
;             const float l0 = LSE[tok * 12 + hs], l1 = LSE[tok * 12 + 4 + hs], l2 = LSE[tok * 12 + 8 + hs];
;             const float mx = fmaxf(l0, fmaxf(l1, l2)); float w0 = __expf(l0 - mx), w1 = __expf(l1 - mx), w2 = __expf(l2 - mx); const float inv = 1.0f / (w0 + w1 + w2); w0 *= inv; w1 *= inv; w2 *= inv;
;             const size_t off = (size_t)tok * 512 + hs * 128 + ch * 8;
;             const v4u o0 = *(const v4u*)(OG + off), o1 = *(const v4u*)(OG + (size_t)TH * 512 + off), o2 = *(const v4u*)(OG + (size_t)2 * TH * 512 + off);
;             v4u r;
;             r.x = pk2(w0 * lo_f(o0.x) + w1 * lo_f(o1.x) + w2 * lo_f(o2.x), w0 * hi_f(o0.x) + w1 * hi_f(o1.x) + w2 * hi_f(o2.x));
;             r.y = pk2(w0 * lo_f(o0.y) + w1 * lo_f(o1.y) + w2 * lo_f(o2.y), w0 * hi_f(o0.y) + w1 * hi_f(o1.y) + w2 * hi_f(o2.y));
;             r.z = pk2(w0 * lo_f(o0.z) + w1 * lo_f(o1.z) + w2 * lo_f(o2.z), w0 * hi_f(o0.z) + w1 * hi_f(o1.z) + w2 * hi_f(o2.z));
;             r.w = pk2(w0 * lo_f(o0.w) + w1 * lo_f(o1.w) + w2 * lo_f(o2.w), w0 * hi_f(o0.w) + w1 * hi_f(o1.w) + w2 * hi_f(o2.w));
;             *(v4u*)(ATT + off) = r;
;         } }
.LBB0_491:
	s_or_b64 exec, exec, s[0:1]
	s_waitcnt lgkmcnt(0)
	v_mov_b32_e32 v2, v188
	v_readlane_b32 s0, v254, 39
	s_nop 0
	s_and_b32 s98, s0, 7
	s_add_i32 s99, s98, 1
	s_lshl_b32 s99, s99, 18
	s_add_i32 s99, s99, -1
	s_lshl_b32 s98, s98, 18
	s_lshr_b32 s0, s0, 3
	s_lshl_b32 s0, s0, 9
	s_or_b32 s0, s0, s98
	s_barrier
	s_nop 0
	v_add_u32_e32 v0, s0, v2
	s_mov_b32 s0, 0x200000
	v_cmp_gt_i32_e32 vcc, s0, v0
	s_and_saveexec_b64 s[0:1], vcc
	v_readlane_b32 s6, v253, 49
	s_cbranch_execz .LBB0_494
	v_readlane_b32 s2, v253, 48
	s_nop 1
	v_lshl_add_u32 v2, v2, 3, s2
	s_mov_b64 s[2:3], 0
.LBB0_493:
	v_ashrrev_i32_e32 v4, 6, v0
	v_bfe_u32 v3, v0, 4, 2
	v_mul_lo_u32 v5, v4, 12
	v_or_b32_e32 v6, v5, v3
	v_ashrrev_i32_e32 v7, 31, v6
	v_lshl_add_u64 v[8:9], v[6:7], 2, s[90:91]
	global_load_dword v5, v[8:9], off
	v_add_u32_e32 v8, 4, v6
	v_add_u32_e32 v6, 8, v6
	v_ashrrev_i32_e32 v9, 31, v8
	v_ashrrev_i32_e32 v7, 31, v6
	v_lshl_add_u64 v[8:9], v[8:9], 2, s[90:91]
	v_lshl_add_u64 v[6:7], v[6:7], 2, s[90:91]
	global_load_dword v8, v[8:9], off
	v_lshlrev_b32_e32 v3, 7, v3
	global_load_dword v6, v[6:7], off
	v_add_u32_e32 v0, 0x4000, v0
	v_mov_b32_e32 v28, v4
	v_ashrrev_i32_e32 v29, 31, v4
	v_lshlrev_b64 v[28:29], 9, v[28:29]
	v_and_b32_e32 v30, 0x78, v2
	v_or3_b32 v28, v28, v3, v30
	v_lshlrev_b64 v[20:21], 1, v[28:29]
	v_lshl_add_u64 v[32:33], s[88:89], 0, v[20:21]
	v_lshl_add_u64 v[34:35], s[30:31], 0, v[20:21]
	v_lshl_add_u64 v[36:37], s[48:49], 0, v[20:21]
	global_load_dwordx4 v[40:43], v[32:33], off
	global_load_dwordx4 v[44:47], v[34:35], off
	global_load_dwordx4 v[48:51], v[36:37], off
	v_ashrrev_i32_e32 v52, 6, v0
	v_bfe_u32 v54, v0, 4, 2
	v_ashrrev_i32_e32 v53, 31, v52
	v_add_u32_e32 v55, s6, v2
	v_lshlrev_b64 v[52:53], 9, v[52:53]
	v_lshlrev_b32_e32 v54, 7, v54
	v_and_b32_e32 v55, 0x78, v55
	v_or3_b32 v52, v52, v54, v55
	v_lshlrev_b64 v[52:53], 1, v[52:53]
	v_lshl_add_u64 v[54:55], s[88:89], 0, v[52:53]
	v_lshl_add_u64 v[56:57], s[30:31], 0, v[52:53]
	v_lshl_add_u64 v[58:59], s[48:49], 0, v[52:53]
	global_load_dword v60, v[54:55], off
	global_load_dword v60, v[56:57], off
	global_load_dword v60, v[58:59], off
	s_waitcnt vmcnt(6)
	v_max3_f32 v7, v5, v8, v6
	v_sub_f32_e32 v5, v5, v7
	v_mul_f32_e32 v5, 0x3fb8aa3b, v5
	v_exp_f32_e32 v17, v5
	v_sub_f32_e32 v5, v8, v7
	v_mul_f32_e32 v5, 0x3fb8aa3b, v5
	v_sub_f32_e32 v6, v6, v7
	v_exp_f32_e32 v5, v5
	v_mul_f32_e32 v6, 0x3fb8aa3b, v6
	v_exp_f32_e32 v16, v6
	v_add_f32_e32 v6, v17, v5
	v_add_f32_e32 v6, v16, v6
	v_div_scale_f32 v7, s[4:5], v6, v6, 1.0
	v_rcp_f32_e32 v8, v7
	s_mov_b32 s4, s99
	v_fma_f32 v9, -v7, v8, 1.0
	v_fmac_f32_e32 v8, v9, v8
	v_div_scale_f32 v9, vcc, 1.0, v6, 1.0
	v_mul_f32_e32 v10, v9, v8
	v_fma_f32 v11, -v7, v10, v9
	v_fmac_f32_e32 v10, v11, v8
	v_fma_f32 v7, -v7, v10, v9
	v_div_fmas_f32 v7, v7, v8, v10
	v_div_fixup_f32 v18, v7, v6, 1.0
	v_mul_f32_e32 v19, v5, v18
	s_waitcnt vmcnt(3)
	v_mov_b32_e32 v4, v40
	v_mov_b32_e32 v5, v41
	v_mov_b32_e32 v6, v42
	v_mov_b32_e32 v7, v43
	v_mov_b32_e32 v8, v44
	v_mov_b32_e32 v9, v45
	v_mov_b32_e32 v10, v46
	v_mov_b32_e32 v11, v47
	v_mov_b32_e32 v12, v48
	v_mov_b32_e32 v13, v49
	v_mov_b32_e32 v14, v50
	v_mov_b32_e32 v15, v51
	v_cmp_lt_i32_e32 vcc, s4, v0
	v_add_u32_e32 v2, s6, v2
	s_or_b64 s[2:3], vcc, s[2:3]
	v_lshlrev_b32_e32 v3, 16, v8
	v_and_b32_e32 v22, 0xffff0000, v8
	v_lshlrev_b32_e32 v23, 16, v9
	v_and_b32_e32 v24, 0xffff0000, v9
	v_pk_mul_f32 v[8:9], v[16:17], v[18:19] op_sel_hi:[1,0]
	v_lshlrev_b32_e32 v17, 16, v4
	v_lshlrev_b32_e32 v16, 16, v12
	v_pk_mul_f32 v[16:17], v[8:9], v[16:17]
	v_lshlrev_b32_e32 v25, 16, v10
	v_fma_f32 v3, v19, v3, v17
	v_add_f32_e32 v3, v16, v3
	v_and_b32_e32 v17, 0xffff0000, v4
	v_and_b32_e32 v16, 0xffff0000, v12
	v_pk_mul_f32 v[16:17], v[8:9], v[16:17]
	v_and_b32_e32 v10, 0xffff0000, v10
	v_fma_f32 v4, v19, v22, v17
	v_add_f32_e32 v4, v16, v4
	v_lshlrev_b32_e32 v17, 16, v5
	v_lshlrev_b32_e32 v16, 16, v13
	v_pk_mul_f32 v[16:17], v[8:9], v[16:17]
	v_cvt_pk_bf16_f32 v4, v3, v4
	v_lshlrev_b32_e32 v26, 16, v11
	v_fma_f32 v3, v19, v23, v17
	v_add_f32_e32 v3, v16, v3
	v_and_b32_e32 v17, 0xffff0000, v5
	v_and_b32_e32 v16, 0xffff0000, v13
	v_pk_mul_f32 v[12:13], v[8:9], v[16:17]
	s_nop 0
	v_fma_f32 v5, v19, v24, v13
	v_add_f32_e32 v5, v12, v5
	v_lshlrev_b32_e32 v13, 16, v6
	v_lshlrev_b32_e32 v12, 16, v14
	v_pk_mul_f32 v[12:13], v[8:9], v[12:13]
	v_cvt_pk_bf16_f32 v5, v3, v5
	s_nop 0
	v_fma_f32 v3, v19, v25, v13
	v_add_f32_e32 v3, v12, v3
	v_and_b32_e32 v13, 0xffff0000, v6
	v_and_b32_e32 v12, 0xffff0000, v14
	v_pk_mul_f32 v[12:13], v[8:9], v[12:13]
	s_nop 0
	v_fma_f32 v6, v19, v10, v13
	v_add_f32_e32 v6, v12, v6
	v_lshlrev_b32_e32 v13, 16, v7
	v_lshlrev_b32_e32 v12, 16, v15
	v_pk_mul_f32 v[12:13], v[8:9], v[12:13]
	v_cvt_pk_bf16_f32 v6, v3, v6
	v_and_b32_e32 v10, 0xffff0000, v15
	v_fma_f32 v3, v19, v26, v13
	v_add_f32_e32 v3, v12, v3
	v_and_b32_e32 v12, 0xffff0000, v11
	v_and_b32_e32 v11, 0xffff0000, v7
	v_pk_mul_f32 v[8:9], v[8:9], v[10:11]
	s_nop 0
	v_fma_f32 v7, v19, v12, v9
	v_add_f32_e32 v7, v8, v7
	v_lshl_add_u64 v[8:9], s[92:93], 0, v[20:21]
	v_cvt_pk_bf16_f32 v7, v3, v7
	global_store_dwordx4 v[8:9], v[4:7], off
	s_andn2_b64 exec, exec, s[2:3]
	s_cbranch_execnz .LBB0_493

; __device__ __forceinline__ unsigned xb_ld(unsigned* p)              { return __hip_atomic_load(p, __ATOMIC_RELAXED, __HIP_MEMORY_SCOPE_AGENT); }
; __device__ __forceinline__ unsigned xb_add(unsigned* p, unsigned v) { return __hip_atomic_fetch_add(p, v, __ATOMIC_RELAXED, __HIP_MEMORY_SCOPE_AGENT); }
; #define XB_SPIN(cond, bar) do { unsigned _sp = 0; while (cond) { __builtin_amdgcn_s_sleep(1); \
;     if ((++_sp & 255u) == 0u) { if (xb_ld(&(bar)[XB_TMO])) break; if (_sp > XB_SPIN_CAP) { atomicAdd(&(bar)[XB_TMO], 1u); break; } } } } while (0)
; __device__ __forceinline__ void xcd_barrier(const XcdBarrier& b) {
;     ...
;         const unsigned old = xb_add(&bar[XB_XSUB(b.x)], 1u);
;         const unsigned gen = old / nloc;
;         if (old + 1u == (gen + 1u) * nloc) {
;             __builtin_amdgcn_fence(__ATOMIC_RELEASE, "agent");
;             asm volatile("s_waitcnt vmcnt(0)" ::: "memory");
;             const unsigned og = xb_add(&bar[XB_TOP], 1u);
;             const unsigned tg = og / nx;
;             if (og + 1u == (tg + 1u) * nx) xb_add(&bar[XB_TOPGEN], 1u);
;             else XB_SPIN(xb_ld(&bar[XB_TOPGEN]) == tg, bar);
.LBB0_526:
	s_andn2_saveexec_b64 s[4:5], s[4:5]
	s_cbranch_execz .LBB0_546
	s_mov_b64 s[4:5], exec
	buffer_wbl2 sc1
	s_waitcnt lgkmcnt(0)
	s_waitcnt vmcnt(0)
	v_readlane_b32 s100, v252, 26
	v_readlane_b32 s101, v252, 27
	s_nop 4
	global_load_dwordx4 v[4:7], v1, s[100:101] offset:32 sc1
	global_load_dwordx4 v[8:11], v1, s[100:101] offset:48 sc1
	s_waitcnt vmcnt(0)
	v_add_u32_e32 v12, -1, v4
	v_and_b32_e32 v12, v12, v4
	v_min_u32_e32 v13, v4, v5
	v_add_u32_e32 v14, -1, v5
	v_and_or_b32 v12, v14, v5, v12
	v_min_u32_e32 v13, v13, v5
	v_add_u32_e32 v14, -1, v6
	v_and_or_b32 v12, v14, v6, v12
	v_min_u32_e32 v13, v13, v6
	v_add_u32_e32 v14, -1, v7
	v_and_or_b32 v12, v14, v7, v12
	v_min_u32_e32 v13, v13, v7
	v_add_u32_e32 v14, -1, v8
	v_and_or_b32 v12, v14, v8, v12
	v_min_u32_e32 v13, v13, v8
	v_add_u32_e32 v14, -1, v9
	v_and_or_b32 v12, v14, v9, v12
	v_min_u32_e32 v13, v13, v9
	v_add_u32_e32 v14, -1, v10
	v_and_or_b32 v12, v14, v10, v12
	v_min_u32_e32 v13, v13, v10
	v_add_u32_e32 v14, -1, v11
	v_and_or_b32 v12, v14, v11, v12
	v_min_u32_e32 v13, v13, v11
	v_cmp_eq_u32_e32 vcc, 0, v13
	s_nop 1
	v_cndmask_b32_e64 v13, 0, 1, vcc
	v_or_b32_e32 v12, v12, v13
	s_nop 0
	v_readfirstlane_b32 s98, v12
	s_cmp_eq_u32 s98, 0
	s_cbranch_scc1 .LBB0_543
	v_mbcnt_lo_u32_b32 v0, s4, 0
	v_mbcnt_hi_u32_b32 v0, s5, v0
	v_cmp_eq_u32_e32 vcc, 0, v0
	s_and_saveexec_b64 s[6:7], vcc
	s_cbranch_execz .LBB0_529
	s_bcnt1_i32_b64 s4, s[4:5]
	v_mov_b32_e32 v3, s4
	v_readlane_b32 s4, v252, 24
	v_readlane_b32 s5, v252, 25
	s_nop 4
	global_atomic_add v3, v1, v3, s[4:5] sc0
